# MLP-down tail tiles: 32 split-K parts of 4 K-tiles (one per workgroup) instead of 8 parts of 16 on 64 workgroups; fix-up sums 32 partials for the 64 real rows (on v83)
# speedup vs baseline: 1.0302x; 1.0118x over previous
.LBB0_59:
	s_or_b64 exec, exec, s[4:5]
	s_add_u32 s4, s76, 0x800
	s_addc_u32 s5, s77, 0
	v_writelane_b32 v252, s4, 39
	s_add_u32 s3, s76, 0x10120000
	v_lshrrev_b32_e32 v165, 4, v164
	v_writelane_b32 v252, s5, 40
	v_writelane_b32 v252, s3, 41
	s_addc_u32 s3, s77, 0
	v_writelane_b32 v252, s3, 42
	s_add_u32 s3, s76, 0x10340000
	v_writelane_b32 v252, s3, 43
	s_addc_u32 s3, s77, 0
	s_add_u32 s4, s76, 0x1300000
	v_writelane_b32 v252, s3, 44
	s_addc_u32 s5, s77, 0
	v_writelane_b32 v252, s4, 45
	v_mbcnt_lo_u32_b32 v209, -1, 0
	v_lshl_add_u32 v204, v164, 4, 0
	v_writelane_b32 v252, s5, 46
	s_add_u32 s4, s76, 0x1b00000
	s_addc_u32 s5, s77, 0
	v_writelane_b32 v252, s4, 47
	v_mov_b32_e32 v205, 0x358637bd
	v_mov_b32_e32 v211, 1
	v_writelane_b32 v252, s5, 48
	s_add_u32 s4, s76, 0x3b00000
	s_addc_u32 s5, s77, 0
	v_writelane_b32 v252, s4, 49
	v_mov_b32_e32 v208, 0x3c23d70a
	v_mbcnt_hi_u32_b32 v210, -1, v209
	v_writelane_b32 v252, s5, 50
	s_add_u32 s4, s76, 0x5b00000
	s_addc_u32 s5, s77, 0
	v_writelane_b32 v252, s4, 51
	v_mov_b32_e32 v112, 0
	v_mov_b32_e32 v212, 0xf149f2ca
	v_writelane_b32 v252, s5, 52
	s_add_u32 s4, s76, 0x7300000
	s_addc_u32 s5, s77, 0
	v_writelane_b32 v252, s4, 53
	v_mov_b64_e32 v[174:175], 0xff
	v_mov_b64_e32 v[176:177], 0x440
	v_writelane_b32 v252, s5, 54
	s_add_u32 s4, s76, 0x7b00000
	s_addc_u32 s5, s77, 0
	v_writelane_b32 v252, s4, 55
	v_mov_b64_e32 v[178:179], 0x43f
	v_mov_b64_e32 v[180:181], 0x200
	v_writelane_b32 v252, s5, 56
	s_add_u32 s4, s76, 0x9b00000
	s_addc_u32 s5, s77, 0
	s_add_u32 s10, s76, 0x12100000
	s_addc_u32 s11, s77, 0
	s_add_u32 s86, s76, 0x16500000
	v_writelane_b32 v252, s4, 57
	s_addc_u32 s87, s77, 0
	v_mov_b64_e32 v[182:183], 0x1ff
	v_writelane_b32 v252, s5, 58
	s_add_u32 s4, s76, 0x18700000
	s_addc_u32 s5, s77, 0
	v_writelane_b32 v252, s4, 59
	s_add_u32 s26, s76, 0x1a900000
	s_addc_u32 s27, s77, 0
	v_writelane_b32 v252, s5, 60
	s_ashr_i32 s31, s82, 31
	v_readlane_b32 s36, v252, 23
	s_ashr_i32 s3, s2, 31
	v_readlane_b32 s44, v252, 31
	v_readlane_b32 s45, v252, 32
	s_add_u32 s4, s44, 0x4000000
	s_addc_u32 s5, s45, 0
	v_readlane_b32 s37, v252, 24
	v_readlane_b32 s38, v252, 25
	v_readlane_b32 s39, v252, 26
	v_readlane_b32 s40, v252, 27
	v_readlane_b32 s41, v252, 28
	v_readlane_b32 s42, v252, 29
	v_readlane_b32 s43, v252, 30
	v_readlane_b32 s46, v252, 33
	v_readlane_b32 s47, v252, 34
	v_readlane_b32 s48, v252, 35
	v_readlane_b32 s49, v252, 36
	v_readlane_b32 s50, v252, 37
	v_readlane_b32 s51, v252, 38
	v_writelane_b32 v252, s4, 61
	s_add_u32 s18, s42, 0x2000
	s_addc_u32 s19, s43, 0
	v_writelane_b32 v252, s5, 62
	s_movk_i32 s91, 0x6000
	v_readlane_b32 s34, v252, 22
	s_lshl_b32 s74, s34, 2
	s_cmp_lg_u64 s[42:43], 0
	s_cselect_b64 s[20:21], -1, 0
	s_add_u32 s84, s76, 0x40200
	s_addc_u32 s85, s77, 0
	s_add_u32 s58, s76, 0x40400
	s_addc_u32 s59, s77, 0
	s_add_u32 s60, s76, 0x40500
	s_addc_u32 s61, s77, 0
	s_add_u32 s62, s76, 0x40600
	s_addc_u32 s63, s77, 0
	s_add_u32 s56, s76, 0x40700
	s_addc_u32 s57, s77, 0
	s_add_u32 s22, s76, 0x40800
	s_addc_u32 s23, s77, 0
	s_add_u32 s4, s76, 0x40900
	s_addc_u32 s5, s77, 0
	v_writelane_b32 v252, s4, 63
	v_writelane_b32 v255, s84, 0
	s_movk_i32 s94, 0x1fff
	v_writelane_b32 v253, s5, 0
	s_add_u32 s4, s76, 0x40a00
	s_addc_u32 s5, s77, 0
	v_writelane_b32 v253, s4, 1
	v_writelane_b32 v255, s85, 1
	v_writelane_b32 v255, s58, 2
	v_writelane_b32 v253, s5, 2
	s_add_u32 s4, s76, 0x40b00
	s_addc_u32 s5, s77, 0
	v_writelane_b32 v253, s4, 3
	v_writelane_b32 v255, s59, 3
	v_writelane_b32 v255, s60, 4
	v_writelane_b32 v253, s5, 4
	s_add_u32 s4, s76, 0x40c00
	s_addc_u32 s5, s77, 0
	v_writelane_b32 v253, s4, 5
	v_writelane_b32 v255, s61, 5
	v_writelane_b32 v255, s62, 6
	v_writelane_b32 v253, s5, 6
	s_add_u32 s4, s76, 0x40d00
	s_addc_u32 s5, s77, 0
	v_writelane_b32 v253, s4, 7
	v_writelane_b32 v255, s63, 7
	v_writelane_b32 v255, s56, 8
	v_writelane_b32 v253, s5, 8
	s_add_u32 s4, s76, 0x40e00
	s_addc_u32 s5, s77, 0
	v_writelane_b32 v253, s4, 9
	v_writelane_b32 v255, s57, 9
	s_nop 0
	v_writelane_b32 v253, s5, 10
	s_add_u32 s4, s76, 0x40f00
	s_addc_u32 s5, s77, 0
	v_writelane_b32 v253, s4, 11
	s_nop 1
	v_writelane_b32 v253, s5, 12
	s_add_u32 s4, s76, 0x41000
	s_addc_u32 s5, s77, 0
	v_writelane_b32 v253, s4, 13
	s_nop 1
	v_writelane_b32 v253, s5, 14
	s_add_u32 s4, s76, 0x41100
	s_addc_u32 s5, s77, 0
	v_writelane_b32 v253, s4, 15
	s_nop 1
	v_writelane_b32 v253, s5, 16
	s_add_u32 s4, s76, 0x41200
	s_addc_u32 s5, s77, 0
	v_writelane_b32 v253, s4, 17
	s_nop 1
	v_writelane_b32 v253, s5, 18
	s_add_u32 s4, s76, 0x41300
	s_addc_u32 s5, s77, 0
	v_writelane_b32 v253, s4, 19
	s_cmp_eq_u32 s8, 15
	s_nop 0
	v_writelane_b32 v253, s5, 20
	s_cselect_b64 s[4:5], -1, 0
	v_writelane_b32 v253, s4, 21
	s_cmp_eq_u32 s8, 14
	s_nop 0
	v_writelane_b32 v253, s5, 22
	s_cselect_b64 s[4:5], -1, 0
	v_writelane_b32 v253, s4, 23
	s_cmp_eq_u32 s8, 13
	s_nop 0
	v_writelane_b32 v253, s5, 24
	s_cselect_b64 s[4:5], -1, 0
	v_writelane_b32 v253, s4, 25
	s_cmp_eq_u32 s8, 12
	s_nop 0
	v_writelane_b32 v253, s5, 26
	s_cselect_b64 s[4:5], -1, 0
	v_writelane_b32 v253, s4, 27
	s_cmp_eq_u32 s8, 11
	s_nop 0
	v_writelane_b32 v253, s5, 28
	s_cselect_b64 s[4:5], -1, 0
	v_writelane_b32 v253, s4, 29
	s_cmp_eq_u32 s8, 10
	s_nop 0
	v_writelane_b32 v253, s5, 30
	s_cselect_b64 s[4:5], -1, 0
	v_writelane_b32 v253, s4, 31
	s_cmp_eq_u32 s8, 9
	s_nop 0
	v_writelane_b32 v253, s5, 32
	s_cselect_b64 s[4:5], -1, 0
	v_writelane_b32 v253, s4, 33
	s_cmp_eq_u32 s8, 8
	s_nop 0
	v_writelane_b32 v253, s5, 34
	s_cselect_b64 s[4:5], -1, 0
	v_writelane_b32 v253, s4, 35
	s_cmp_eq_u32 s8, 7
	s_nop 0
	v_writelane_b32 v253, s5, 36
	s_cselect_b64 s[4:5], -1, 0
	v_writelane_b32 v253, s4, 37
	s_cmp_eq_u32 s8, 6
	s_nop 0
	v_writelane_b32 v253, s5, 38
	s_cselect_b64 s[4:5], -1, 0
	v_writelane_b32 v253, s4, 39
	s_cmp_eq_u32 s8, 5
	s_nop 0
	v_writelane_b32 v253, s5, 40
	s_cselect_b64 s[4:5], -1, 0
	v_writelane_b32 v253, s4, 41
	s_cmp_eq_u32 s8, 4
	s_nop 0
	v_writelane_b32 v253, s5, 42
	s_cselect_b64 s[4:5], -1, 0
	v_writelane_b32 v253, s4, 43
	s_cmp_eq_u32 s8, 3
	s_nop 0
	v_writelane_b32 v253, s5, 44
	s_cselect_b64 s[4:5], -1, 0
	v_writelane_b32 v253, s4, 45
	s_cmp_eq_u32 s8, 2
	s_nop 0
	v_writelane_b32 v253, s5, 46
	s_cselect_b64 s[4:5], -1, 0
	v_writelane_b32 v253, s4, 47
	s_cmp_eq_u32 s8, 1
	s_nop 0
	v_writelane_b32 v253, s5, 48
	s_cselect_b64 s[4:5], -1, 0
	v_writelane_b32 v253, s4, 49
	s_cmp_eq_u32 s8, 0
	s_nop 0
	v_writelane_b32 v253, s5, 50
	s_cselect_b64 s[4:5], -1, 0
	v_writelane_b32 v253, s4, 51
	s_nop 1
	v_writelane_b32 v253, s5, 52
	s_lshl_b32 s4, s9, 2
	s_add_u32 s4, s16, s4
	s_addc_u32 s5, s17, 0
	s_add_u32 s6, s4, 0x1400
	s_addc_u32 s7, s5, 0
	v_writelane_b32 v253, s6, 53
	s_add_u32 s4, s4, 0x2400
	s_addc_u32 s5, s5, 0
	v_writelane_b32 v253, s7, 54
	v_writelane_b32 v253, s4, 55
	s_nop 1
	v_writelane_b32 v253, s5, 56
	s_add_u32 s4, s76, 0x43400
	s_addc_u32 s5, s77, 0
	v_writelane_b32 v253, s4, 57
	s_nop 1
	v_writelane_b32 v253, s5, 58
	s_add_u32 s4, s76, 0x43500
	s_addc_u32 s5, s77, 0
	v_writelane_b32 v253, s4, 59
	s_lshr_b32 s6, s25, 7
	s_bfe_u32 s7, s25, 0x10006
	v_writelane_b32 v253, s5, 60
	s_lshl_b32 s4, s34, 4
	s_and_b32 s28, s4, 0x3fffffe0
	s_lshl_b32 s4, s6, 14
	s_add_i32 s4, s4, 0
	v_writelane_b32 v253, s4, 61
	s_lshl_b32 s4, s2, 9
	v_writelane_b32 v253, s4, 62
	s_lshl_b32 s5, s7, 1
	s_lshl_b32 s4, s7, 6
	s_lshl_b32 s90, s7, 14
	s_add_i32 s29, 0, 0x20080
	s_and_b32 s8, 64, s25
	s_lshl_b32 s36, s82, 9
	s_cmp_eq_u32 s7, 0
	s_cselect_b64 s[12:13], -1, 0
	s_cmp_lg_u32 s8, 0
	v_writelane_b32 v253, s12, 63
	s_cselect_b64 s[8:9], -1, 0
	s_lshl_b32 s6, s6, 5
	v_writelane_b32 v254, s13, 0
	v_writelane_b32 v254, s8, 1
	s_cmpk_lt_i32 s2, 0x120
	v_lshl_add_u32 v203, v164, 2, s29
	v_writelane_b32 v254, s9, 2
	v_writelane_b32 v254, s6, 3
	s_cselect_b64 s[6:7], -1, 0
	v_writelane_b32 v254, s6, 4
	s_lshl_b32 s14, s2, 3
	s_add_i32 s16, s34, s14
	v_writelane_b32 v254, s7, 5
	s_lshr_b32 s6, s3, 29
	s_add_i32 s6, s2, s6
	s_ashr_i32 s30, s6, 3
	s_lshl_b32 s7, s2, 5
	s_mul_i32 s8, s30, 0xffffff01
	s_add_i32 s7, s8, s7
	s_ashr_i32 s8, s7, 31
	s_lshr_b32 s8, s8, 26
	s_add_i32 s8, s7, s8
	s_and_b32 s9, s8, 0xffffffc0
	s_sub_i32 s7, s7, s9
	s_bfe_i32 s9, s7, 0x80000
	s_bfe_u32 s9, s9, 0x3000c
	s_add_i32 s9, s7, s9
	s_and_b32 s12, s9, 0xf8
	s_sub_i32 s7, s7, s12
	s_ashr_i32 s8, s8, 6
	s_lshl_b32 s8, s8, 3
	s_sext_i32_i8 s7, s7
	s_add_i32 s8, s8, s7
	s_bfe_i32 s7, s9, 0x80000
	s_sext_i32_i16 s7, s7
	s_and_b32 s9, s2, 3
	s_lshl_b32 s14, s16, 6
	s_ashr_i32 s7, s7, 3
	s_bfe_u32 s12, s2, 0x30002
	s_lshl_b32 s13, s9, 10
	s_lshl_b32 s73, s82, 3
	v_writelane_b32 v254, s14, 6
	s_mov_b32 s14, s16
	v_writelane_b32 v254, s14, 7
	s_cmpk_lt_i32 s16, 0x800
	s_nop 0
	v_writelane_b32 v254, s15, 8
	s_cselect_b64 s[14:15], -1, 0
	v_writelane_b32 v254, s14, 9
	s_cmpk_lt_i32 s2, 0x420
	s_nop 0
	v_writelane_b32 v254, s15, 10
	s_cselect_b64 s[14:15], -1, 0
	s_and_b32 s6, s6, -8
	v_writelane_b32 v254, s14, 11
	s_sub_i32 s33, s2, s6
	s_nop 0
	v_writelane_b32 v254, s15, 12
	s_add_u32 s14, s46, 0x4000000
	s_addc_u32 s15, s47, 0
	v_readlane_b32 s40, v252, 0
	v_readlane_b32 s52, v252, 12
	v_readlane_b32 s53, v252, 13
	v_readlane_b32 s50, v252, 10
	v_readlane_b32 s51, v252, 11
	s_cmp_lg_u64 s[52:53], 0
	v_writelane_b32 v254, s14, 13
	s_cselect_b64 s[50:51], -1, 0
	s_cmpk_lt_i32 s2, 0x140
	v_writelane_b32 v254, s15, 14
	s_cselect_b64 s[14:15], -1, 0
	v_writelane_b32 v254, s14, 15
	s_bfe_u32 s6, s25, 0x30006
	s_lshl_b32 s17, s6, 8
	v_writelane_b32 v254, s15, 16
	s_and_b32 s14, s2, 7
	v_writelane_b32 v254, s17, 17
	s_lshl_b32 s17, s6, 2
	v_readlane_b32 s54, v252, 14
	v_readlane_b32 s55, v252, 15
	s_bfe_u32 s15, s2, 0x30003
	s_lshl_b32 s16, s14, 11
	v_writelane_b32 v254, s17, 18
	s_lshl_b32 s17, s6, 20
	s_mov_b64 s[54:55], s[22:23]
	s_add_u32 s22, s26, s17
	s_addc_u32 s23, s27, 0
	s_cmp_lt_i32 s33, 0
	s_movk_i32 s17, 0x85
	s_movk_i32 s17, 0x80
	s_mul_i32 s17, s33, s17
	v_writelane_b32 v254, s22, 19
	s_add_i32 s17, s17, s30
	s_add_i32 s22, s2, 0x320
	s_cmpk_ge_u32 s2, 0xe0
	s_cselect_b32 s17, s22, s17
	v_writelane_b32 v255, s54, 10
	v_writelane_b32 v254, s23, 20
	s_ashr_i32 s22, s17, 31
	s_lshr_b32 s22, s22, 24
	s_add_i32 s22, s17, s22
	s_and_b32 s23, s22, 0xffffff00
	s_ashr_i32 s22, s22, 8
	s_lshl_b32 s22, s22, 3
	s_sub_i32 s17, s17, s23
	s_sub_i32 s23, 33, s22
	s_min_i32 s23, s23, 8
	v_writelane_b32 v254, s33, 21
	s_cmpk_lt_i32 s2, 0x100
	v_writelane_b32 v254, s30, 22
	s_cselect_b32 s88, 0, s13
	v_writelane_b32 v254, s88, 23
	s_cselect_b32 s12, s7, s12
	s_cselect_b32 s7, s7, s15
	v_writelane_b32 v254, s89, 24
	v_writelane_b32 v254, s12, 25
	v_writelane_b32 v254, s7, 26
	s_cselect_b32 s7, s8, 32
	v_writelane_b32 v254, s7, 27
	s_cselect_b32 s7, -1, s9
	v_writelane_b32 v254, s7, 28
	s_cselect_b32 s7, -1, s14
	v_writelane_b32 v254, s7, 29
	s_cselect_b32 s7, 32, 8
	v_writelane_b32 v254, s7, 30
	s_cselect_b32 s7, 0x80, 16
	v_writelane_b32 v254, s7, 31
	s_sext_i32_i16 s7, s23
	v_cvt_f32_i32_e32 v0, s7
	v_cvt_f32_i32_e32 v1, s17
	s_cselect_b32 s88, 0, s16
	s_lshl_b32 s6, s6, 23
	v_rcp_iflag_f32_e32 v2, v0
	s_add_u32 s8, s26, s6
	v_writelane_b32 v254, s26, 32
	s_addc_u32 s9, s27, 0
	v_mul_f32_e32 v2, v1, v2
	v_writelane_b32 v254, s27, 33
	s_xor_b32 s6, s17, s7
	v_trunc_f32_e32 v2, v2
	v_writelane_b32 v254, s8, 34
	s_ashr_i32 s6, s6, 30
	v_fma_f32 v1, -v2, v0, v1
	v_writelane_b32 v254, s9, 35
	s_or_b32 s8, s6, 1
	v_cmp_ge_f32_e64 s[6:7], |v1|, |v0|
	v_cvt_i32_f32_e32 v0, v2
	s_and_b64 s[6:7], s[6:7], exec
	s_mul_i32 s6, s83, s82
	s_mul_i32 s6, s6, s24
	v_writelane_b32 v254, s6, 36
	s_cselect_b32 s6, s8, 0
	v_readfirstlane_b32 s7, v0
	s_add_i32 s6, s7, s6
	s_mul_i32 s7, s6, s23
	s_sub_i32 s7, s17, s7
	s_sext_i32_i16 s7, s7
	s_add_i32 s7, s22, s7
	v_writelane_b32 v254, s7, 37
	v_writelane_b32 v254, s29, 38
	s_sext_i32_i16 s6, s6
	v_writelane_b32 v254, s6, 39
	s_lshl_b32 s6, s34, 7
	v_writelane_b32 v254, s6, 40
	s_add_u32 s6, s76, 0x1a740000
	s_addc_u32 s7, s77, 0
	v_writelane_b32 v254, s6, 41
	s_lshl_b32 s5, s5, 2
	s_lshl_b32 s4, s4, 1
	v_writelane_b32 v254, s7, 42
	v_writelane_b32 v254, s5, 43
	v_writelane_b32 v254, s28, 44
	s_add_i32 s5, s28, 0x800
	v_writelane_b32 v254, s5, 45
	s_add_i32 s5, 0, 0x20040
	v_writelane_b32 v254, s5, 46
	s_add_i32 s5, 0, 0x20044
	v_writelane_b32 v254, s5, 47
	v_writelane_b32 v254, s4, 48
	v_cmp_gt_u32_e64 s[6:7], 3, v164
	s_ashr_i32 s37, s36, 31
	v_writelane_b32 v254, s5, 49
	s_add_i32 s4, 0, 0x20084
	v_writelane_b32 v254, s4, 50
	v_writelane_b32 v254, s6, 51
	s_lshl_b64 s[64:65], s[36:37], 4
	v_writelane_b32 v255, s55, 11
	v_writelane_b32 v254, s7, 52
	v_writelane_b32 v254, s88, 53
	s_lshl_b64 s[6:7], s[36:37], 7
	v_xor_b32_e32 v0, v165, v164
	v_writelane_b32 v254, s89, 54
	v_writelane_b32 v254, s6, 55
	v_writelane_b32 v255, s64, 12
	v_lshlrev_b32_e32 v1, 3, v0
	v_writelane_b32 v254, s7, 56
	s_mov_b64 s[6:7], -1
	v_writelane_b32 v254, s6, 57
	s_lshl_b64 s[92:93], s[36:37], 2
	v_writelane_b32 v255, s65, 13
	v_writelane_b32 v254, s7, 58
	v_writelane_b32 v254, s72, 59
	v_writelane_b32 v254, s73, 60
	v_writelane_b32 v254, s86, 61
	v_and_b32_e32 v2, 56, v1
	v_mov_b32_e32 v0, 0
	v_and_b32_e32 v4, 0x78, v1
	v_writelane_b32 v254, s87, 62
	v_writelane_b32 v255, s92, 14
	v_mov_b32_e32 v113, v0
	v_mov_b32_e32 v114, v0
	v_mov_b32_e32 v115, v0
	v_lshlrev_b32_e32 v166, 1, v4
	v_lshlrev_b32_e32 v168, 1, v2
	s_mov_b32 s83, 0xffff0000
	s_mov_b32 s12, 0x800000
	s_movk_i32 s13, 0x4400
	s_add_i32 s33, 0, 0x20000
	s_mov_b32 s22, 0x40000
	s_movk_i32 s23, 0x7fff
	s_mov_b32 s24, 0x80000
	s_mov_b32 s25, 0xc0000
	s_mov_b32 s29, 0x100000
	s_mov_b32 s14, 0x140000
	s_mov_b32 s15, 0x180000
	s_mov_b32 s28, 0x1c0000
	s_mov_b32 s30, 0x3e38aa3b
	s_mov_b32 s52, 0xf149f2ca
	s_mov_b32 s53, 0xc2800000
	s_mov_b64 s[4:5], 0
	s_mov_b64 s[26:27], 0x80
	s_mov_b32 s66, s89
	v_writelane_b32 v254, s74, 63
	v_writelane_b32 v255, s93, 15
	v_readlane_b32 s41, v252, 1
	v_readlane_b32 s42, v252, 2
	v_readlane_b32 s43, v252, 3
	v_readlane_b32 s44, v252, 4
	v_readlane_b32 s45, v252, 5
	v_readlane_b32 s46, v252, 6
	v_readlane_b32 s47, v252, 7
	v_readlane_b32 s48, v252, 8
	v_readlane_b32 s49, v252, 9
	s_branch .LBB0_63

.LBB0_845:
	s_add_i32 s63, s63, 1
	s_mul_i32 s7, s63, s31
	s_mul_hi_u32 s40, s63, s82
	s_add_i32 s40, s40, s7
	s_mul_i32 s7, s63, s82
	s_add_u32 s46, s7, s2
	s_addc_u32 s47, s40, s3
	v_cmp_gt_i64_e32 vcc, s[46:47], v[182:183]
	v_cmp_lt_i64_e64 s[40:41], s[46:47], v[180:181]
	s_cbranch_vccnz .LBB0_850
	v_cmp_gt_i64_e32 vcc, s[46:47], v[174:175]
	s_mov_b64 s[48:49], -1
	s_cbranch_vccz .LBB0_848
	s_and_b32 s64, s46, 31
	s_lshl_b32 s88, s64, 9
	s_bfe_u32 s44, s46, 0x30005
	s_mov_b64 s[48:49], 0
	s_mov_b64 s[84:85], s[88:89]

.LBB0_851:
	s_mov_b32 s65, 4
	s_mov_b32 s46, 32

.LBB0_876:
	s_lshl_b32 s7, s16, 6
	s_lshl_b32 s6, s6, 5
	s_add_i32 s6, s6, s7
	s_add_i32 s6, s6, s56
	s_addk_i32 s6, 0xf800
	s_ashr_i32 s7, s6, 31
	s_lshl_b64 s[6:7], s[6:7], 18
	s_waitcnt lgkmcnt(0)
	v_lshl_add_u64 v[150:151], v[144:145], 0, s[6:7]
	s_and_b64 vcc, exec, s[42:43]
	s_cbranch_vccz .Lmy_pr_mlpdown_done
	global_store_dwordx4 v[150:151], v[132:135], off
	global_store_dwordx4 v[150:151], v[128:131], off offset:16
	global_store_dwordx4 v[150:151], v[116:119], off offset:512
	global_store_dwordx4 v[150:151], v[102:105], off offset:528
	s_nop 1
	v_add_co_u32_e32 v102, vcc, 0x4000, v150
	s_nop 1
	v_addc_co_u32_e32 v103, vcc, 0, v151, vcc
	global_store_dwordx4 v[102:103], v[124:127], off
	global_store_dwordx4 v[102:103], v[120:123], off offset:16
	global_store_dwordx4 v[102:103], v[94:97], off offset:512
	global_store_dwordx4 v[102:103], v[86:89], off offset:528
	s_nop 1
	v_add_co_u32_e32 v86, vcc, 0x8000, v150
	s_nop 1
	v_addc_co_u32_e32 v87, vcc, 0, v151, vcc
	global_store_dwordx4 v[86:87], v[106:109], off
	global_store_dwordx4 v[86:87], v[98:101], off offset:16
	global_store_dwordx4 v[86:87], v[78:81], off offset:512
	global_store_dwordx4 v[86:87], v[74:77], off offset:528
	s_nop 1
	v_add_co_u32_e32 v74, vcc, 0xc000, v150
	s_nop 1
	v_addc_co_u32_e32 v75, vcc, 0, v151, vcc
	global_store_dwordx4 v[74:75], v[90:93], off
	global_store_dwordx4 v[74:75], v[82:85], off offset:16
	global_store_dwordx4 v[74:75], v[70:73], off offset:512
	global_store_dwordx4 v[74:75], v[66:69], off offset:528
	s_branch .Lmy_pr_mlpdown_done
	s_nop 1
	v_add_co_u32_e32 v66, vcc, 0x20000, v150
	s_nop 1
	v_addc_co_u32_e32 v67, vcc, 0, v151, vcc
	global_store_dwordx4 v[66:67], v[62:65], off
	global_store_dwordx4 v[66:67], v[58:61], off offset:16
	global_store_dwordx4 v[66:67], v[46:49], off offset:512
	global_store_dwordx4 v[66:67], v[38:41], off offset:528
	s_nop 1
	v_add_co_u32_e32 v38, vcc, 0x24000, v150
	s_nop 1
	v_addc_co_u32_e32 v39, vcc, 0, v151, vcc
	global_store_dwordx4 v[38:39], v[54:57], off
	global_store_dwordx4 v[38:39], v[50:53], off offset:16
	global_store_dwordx4 v[38:39], v[30:33], off offset:512
	global_store_dwordx4 v[38:39], v[22:25], off offset:528
	s_nop 1
	v_add_co_u32_e32 v22, vcc, 0x28000, v150
	s_nop 1
	v_addc_co_u32_e32 v23, vcc, 0, v151, vcc
	global_store_dwordx4 v[22:23], v[42:45], off
	global_store_dwordx4 v[22:23], v[34:37], off offset:16
	global_store_dwordx4 v[22:23], v[14:17], off offset:512
	global_store_dwordx4 v[22:23], v[10:13], off offset:528
	s_nop 1
	v_add_co_u32_e32 v10, vcc, 0x2c000, v150
	s_nop 1
	v_addc_co_u32_e32 v11, vcc, 0, v151, vcc
	global_store_dwordx4 v[10:11], v[26:29], off
	global_store_dwordx4 v[10:11], v[18:21], off offset:16
	global_store_dwordx4 v[10:11], v[6:9], off offset:512
	global_store_dwordx4 v[10:11], v[2:5], off offset:528

.LBB0_938:
	s_ashr_i32 s6, s16, 3
	s_cmpk_gt_i32 s6, 63
	s_cselect_b32 s99, 1, 0
	s_add_i32 s4, s6, 0x2000
	s_ashr_i32 s5, s4, 31
	s_lshl_b64 s[34:35], s[4:5], 12
	s_waitcnt lgkmcnt(0)
	v_lshl_add_u64 v[6:7], v[2:3], 0, s[34:35]
	global_load_dwordx2 v[192:193], v[6:7], off
	s_cmp_eq_u32 s99, 1
	s_cbranch_scc1 .Lmy_fx_mlpdown_zero
	s_ashr_i32 s7, s6, 31
	s_lshl_b64 s[6:7], s[6:7], 10
	v_lshl_add_u64 v[22:23], v[4:5], 0, s[6:7]
	s_mov_b32 s100, 0x200000
	global_load_dwordx4 v[32:35], v[22:23], off
	v_add_co_u32_e64 v194, s[38:39], s22, v22
	s_nop 1
	v_addc_co_u32_e64 v195, s[38:39], 0, v23, s[38:39]
	global_load_dwordx4 v[36:39], v[194:195], off
	v_add_co_u32_e64 v194, s[38:39], s24, v22
	s_nop 1
	v_addc_co_u32_e64 v195, s[38:39], 0, v23, s[38:39]
	global_load_dwordx4 v[40:43], v[194:195], off
	v_add_co_u32_e64 v194, s[38:39], s25, v22
	s_nop 1
	v_addc_co_u32_e64 v195, s[38:39], 0, v23, s[38:39]
	global_load_dwordx4 v[44:47], v[194:195], off
	v_add_co_u32_e64 v194, s[38:39], s29, v22
	s_nop 1
	v_addc_co_u32_e64 v195, s[38:39], 0, v23, s[38:39]
	global_load_dwordx4 v[48:51], v[194:195], off
	v_add_co_u32_e64 v194, s[38:39], s14, v22
	s_nop 1
	v_addc_co_u32_e64 v195, s[38:39], 0, v23, s[38:39]
	global_load_dwordx4 v[52:55], v[194:195], off
	v_add_co_u32_e64 v194, s[38:39], s15, v22
	s_nop 1
	v_addc_co_u32_e64 v195, s[38:39], 0, v23, s[38:39]
	global_load_dwordx4 v[56:59], v[194:195], off
	v_add_co_u32_e64 v194, s[38:39], s28, v22
	s_nop 1
	v_addc_co_u32_e64 v195, s[38:39], 0, v23, s[38:39]
	global_load_dwordx4 v[60:63], v[194:195], off
	v_add_co_u32_e64 v196, s[38:39], s100, v22
	s_nop 1
	v_addc_co_u32_e64 v197, s[38:39], 0, v23, s[38:39]
	global_load_dwordx4 v[64:67], v[196:197], off
	v_add_co_u32_e64 v194, s[38:39], s22, v196
	s_nop 1
	v_addc_co_u32_e64 v195, s[38:39], 0, v197, s[38:39]
	global_load_dwordx4 v[68:71], v[194:195], off
	v_add_co_u32_e64 v194, s[38:39], s24, v196
	s_nop 1
	v_addc_co_u32_e64 v195, s[38:39], 0, v197, s[38:39]
	global_load_dwordx4 v[72:75], v[194:195], off
	v_add_co_u32_e64 v194, s[38:39], s25, v196
	s_nop 1
	v_addc_co_u32_e64 v195, s[38:39], 0, v197, s[38:39]
	global_load_dwordx4 v[76:79], v[194:195], off
	v_add_co_u32_e64 v194, s[38:39], s29, v196
	s_nop 1
	v_addc_co_u32_e64 v195, s[38:39], 0, v197, s[38:39]
	global_load_dwordx4 v[80:83], v[194:195], off
	v_add_co_u32_e64 v194, s[38:39], s14, v196
	s_nop 1
	v_addc_co_u32_e64 v195, s[38:39], 0, v197, s[38:39]
	global_load_dwordx4 v[84:87], v[194:195], off
	v_add_co_u32_e64 v194, s[38:39], s15, v196
	s_nop 1
	v_addc_co_u32_e64 v195, s[38:39], 0, v197, s[38:39]
	global_load_dwordx4 v[88:91], v[194:195], off
	v_add_co_u32_e64 v194, s[38:39], s28, v196
	s_nop 1
	v_addc_co_u32_e64 v195, s[38:39], 0, v197, s[38:39]
	global_load_dwordx4 v[92:95], v[194:195], off
	v_add_co_u32_e64 v196, s[38:39], s100, v196
	s_nop 1
	v_addc_co_u32_e64 v197, s[38:39], 0, v197, s[38:39]
	global_load_dwordx4 v[96:99], v[196:197], off
	v_add_co_u32_e64 v194, s[38:39], s22, v196
	s_nop 1
	v_addc_co_u32_e64 v195, s[38:39], 0, v197, s[38:39]
	global_load_dwordx4 v[100:103], v[194:195], off
	v_add_co_u32_e64 v194, s[38:39], s24, v196
	s_nop 1
	v_addc_co_u32_e64 v195, s[38:39], 0, v197, s[38:39]
	global_load_dwordx4 v[104:107], v[194:195], off
	v_add_co_u32_e64 v194, s[38:39], s25, v196
	s_nop 1
	v_addc_co_u32_e64 v195, s[38:39], 0, v197, s[38:39]
	global_load_dwordx4 v[108:111], v[194:195], off
	v_add_co_u32_e64 v194, s[38:39], s29, v196
	s_nop 1
	v_addc_co_u32_e64 v195, s[38:39], 0, v197, s[38:39]
	global_load_dwordx4 v[116:119], v[194:195], off
	v_add_co_u32_e64 v194, s[38:39], s14, v196
	s_nop 1
	v_addc_co_u32_e64 v195, s[38:39], 0, v197, s[38:39]
	global_load_dwordx4 v[120:123], v[194:195], off
	v_add_co_u32_e64 v194, s[38:39], s15, v196
	s_nop 1
	v_addc_co_u32_e64 v195, s[38:39], 0, v197, s[38:39]
	global_load_dwordx4 v[124:127], v[194:195], off
	v_add_co_u32_e64 v194, s[38:39], s28, v196
	s_nop 1
	v_addc_co_u32_e64 v195, s[38:39], 0, v197, s[38:39]
	global_load_dwordx4 v[128:131], v[194:195], off
	v_add_co_u32_e64 v196, s[38:39], s100, v196
	s_nop 1
	v_addc_co_u32_e64 v197, s[38:39], 0, v197, s[38:39]
	global_load_dwordx4 v[132:135], v[196:197], off
	v_add_co_u32_e64 v194, s[38:39], s22, v196
	s_nop 1
	v_addc_co_u32_e64 v195, s[38:39], 0, v197, s[38:39]
	global_load_dwordx4 v[136:139], v[194:195], off
	v_add_co_u32_e64 v194, s[38:39], s24, v196
	s_nop 1
	v_addc_co_u32_e64 v195, s[38:39], 0, v197, s[38:39]
	global_load_dwordx4 v[140:143], v[194:195], off
	v_add_co_u32_e64 v194, s[38:39], s25, v196
	s_nop 1
	v_addc_co_u32_e64 v195, s[38:39], 0, v197, s[38:39]
	global_load_dwordx4 v[144:147], v[194:195], off
	v_add_co_u32_e64 v194, s[38:39], s29, v196
	s_nop 1
	v_addc_co_u32_e64 v195, s[38:39], 0, v197, s[38:39]
	global_load_dwordx4 v[148:151], v[194:195], off
	v_add_co_u32_e64 v194, s[38:39], s14, v196
	s_nop 1
	v_addc_co_u32_e64 v195, s[38:39], 0, v197, s[38:39]
	global_load_dwordx4 v[152:155], v[194:195], off
	v_add_co_u32_e64 v194, s[38:39], s15, v196
	s_nop 1
	v_addc_co_u32_e64 v195, s[38:39], 0, v197, s[38:39]
	global_load_dwordx4 v[156:159], v[194:195], off
	v_add_co_u32_e64 v194, s[38:39], s28, v196
	s_nop 1
	v_addc_co_u32_e64 v195, s[38:39], 0, v197, s[38:39]
	global_load_dwordx4 v[160:163], v[194:195], off
	s_waitcnt vmcnt(0)
	v_lshlrev_b32_e32 v18, 16, v192
	v_and_b32_e32 v19, 0xffff0000, v192
	v_lshlrev_b32_e32 v20, 16, v193
	v_and_b32_e32 v21, 0xffff0000, v193
	v_pk_add_f32 v[18:19], v[32:33], v[18:19]
	v_pk_add_f32 v[20:21], v[34:35], v[20:21]
	v_pk_add_f32 v[18:19], v[36:37], v[18:19]
	v_pk_add_f32 v[20:21], v[38:39], v[20:21]
	v_pk_add_f32 v[18:19], v[40:41], v[18:19]
	v_pk_add_f32 v[20:21], v[42:43], v[20:21]
	v_pk_add_f32 v[18:19], v[44:45], v[18:19]
	v_pk_add_f32 v[20:21], v[46:47], v[20:21]
	v_pk_add_f32 v[18:19], v[48:49], v[18:19]
	v_pk_add_f32 v[20:21], v[50:51], v[20:21]
	v_pk_add_f32 v[18:19], v[52:53], v[18:19]
	v_pk_add_f32 v[20:21], v[54:55], v[20:21]
	v_pk_add_f32 v[18:19], v[56:57], v[18:19]
	v_pk_add_f32 v[20:21], v[58:59], v[20:21]
	v_pk_add_f32 v[18:19], v[60:61], v[18:19]
	v_pk_add_f32 v[20:21], v[62:63], v[20:21]
	v_pk_add_f32 v[18:19], v[64:65], v[18:19]
	v_pk_add_f32 v[20:21], v[66:67], v[20:21]
	v_pk_add_f32 v[18:19], v[68:69], v[18:19]
	v_pk_add_f32 v[20:21], v[70:71], v[20:21]
	v_pk_add_f32 v[18:19], v[72:73], v[18:19]
	v_pk_add_f32 v[20:21], v[74:75], v[20:21]
	v_pk_add_f32 v[18:19], v[76:77], v[18:19]
	v_pk_add_f32 v[20:21], v[78:79], v[20:21]
	v_pk_add_f32 v[18:19], v[80:81], v[18:19]
	v_pk_add_f32 v[20:21], v[82:83], v[20:21]
	v_pk_add_f32 v[18:19], v[84:85], v[18:19]
	v_pk_add_f32 v[20:21], v[86:87], v[20:21]
	v_pk_add_f32 v[18:19], v[88:89], v[18:19]
	v_pk_add_f32 v[20:21], v[90:91], v[20:21]
	v_pk_add_f32 v[18:19], v[92:93], v[18:19]
	v_pk_add_f32 v[20:21], v[94:95], v[20:21]
	v_pk_add_f32 v[18:19], v[96:97], v[18:19]
	v_pk_add_f32 v[20:21], v[98:99], v[20:21]
	v_pk_add_f32 v[18:19], v[100:101], v[18:19]
	v_pk_add_f32 v[20:21], v[102:103], v[20:21]
	v_pk_add_f32 v[18:19], v[104:105], v[18:19]
	v_pk_add_f32 v[20:21], v[106:107], v[20:21]
	v_pk_add_f32 v[18:19], v[108:109], v[18:19]
	v_pk_add_f32 v[20:21], v[110:111], v[20:21]
	v_pk_add_f32 v[18:19], v[116:117], v[18:19]
	v_pk_add_f32 v[20:21], v[118:119], v[20:21]
	v_pk_add_f32 v[18:19], v[120:121], v[18:19]
	v_pk_add_f32 v[20:21], v[122:123], v[20:21]
	v_pk_add_f32 v[18:19], v[124:125], v[18:19]
	v_pk_add_f32 v[20:21], v[126:127], v[20:21]
	v_pk_add_f32 v[18:19], v[128:129], v[18:19]
	v_pk_add_f32 v[20:21], v[130:131], v[20:21]
	v_pk_add_f32 v[18:19], v[132:133], v[18:19]
	v_pk_add_f32 v[20:21], v[134:135], v[20:21]
	v_pk_add_f32 v[18:19], v[136:137], v[18:19]
	v_pk_add_f32 v[20:21], v[138:139], v[20:21]
	v_pk_add_f32 v[18:19], v[140:141], v[18:19]
	v_pk_add_f32 v[20:21], v[142:143], v[20:21]
	v_pk_add_f32 v[18:19], v[144:145], v[18:19]
	v_pk_add_f32 v[20:21], v[146:147], v[20:21]
	v_pk_add_f32 v[18:19], v[148:149], v[18:19]
	v_pk_add_f32 v[20:21], v[150:151], v[20:21]
	v_pk_add_f32 v[18:19], v[152:153], v[18:19]
	v_pk_add_f32 v[20:21], v[154:155], v[20:21]
	v_pk_add_f32 v[18:19], v[156:157], v[18:19]
	v_pk_add_f32 v[20:21], v[158:159], v[20:21]
	v_pk_add_f32 v[18:19], v[160:161], v[18:19]
	v_pk_add_f32 v[20:21], v[162:163], v[20:21]
	s_branch .Lmy_fx_mlpdown_join

.Lmy_fx_mlpdown_join:
	v_mov_b32_e32 v14, v18
	v_mov_b32_e32 v15, v19
	v_mov_b32_e32 v16, v20
	v_mov_b32_e32 v17, v21
	v_mul_f32_e32 v18, v17, v17
	v_mul_f32_e32 v13, v15, v15
	v_fmac_f32_e32 v13, v14, v14
	v_fmac_f32_e32 v18, v16, v16
	v_add_f32_e32 v13, v13, v18
	v_bfe_u32 v18, v14, 16, 1
	v_add3_u32 v14, v14, v18, s23
	v_bfe_u32 v18, v15, 16, 1
	v_lshrrev_b32_e32 v14, 16, v14
	v_add3_u32 v15, v15, v18, s23
	v_and_or_b32 v14, v15, s83, v14
	v_bfe_u32 v15, v16, 16, 1
	v_add3_u32 v15, v16, v15, s23
	v_bfe_u32 v16, v17, 16, 1
	v_lshrrev_b32_e32 v15, 16, v15
	v_add3_u32 v16, v17, v16, s23
	v_and_or_b32 v15, v16, s83, v15
	global_store_dwordx2 v[6:7], v[14:15], off
	ds_bpermute_b32 v6, v1, v13
	s_waitcnt lgkmcnt(0)
	v_add_f32_e32 v6, v13, v6
	ds_bpermute_b32 v7, v8, v6
	s_waitcnt lgkmcnt(0)
	v_add_f32_e32 v6, v6, v7
	ds_bpermute_b32 v7, v9, v6
	s_waitcnt lgkmcnt(0)
	v_add_f32_e32 v6, v6, v7
	ds_bpermute_b32 v7, v10, v6
	s_waitcnt lgkmcnt(0)
	v_add_f32_e32 v6, v6, v7
	ds_bpermute_b32 v7, v11, v6
	s_waitcnt lgkmcnt(0)
	v_add_f32_e32 v6, v6, v7
	ds_bpermute_b32 v7, v12, v6
	s_and_saveexec_b64 s[6:7], vcc
	s_cbranch_execz .LBB0_937
	s_lshl_b64 s[4:5], s[4:5], 7
	s_add_u32 s4, s8, s4
	s_waitcnt lgkmcnt(0)
	v_add_f32_e32 v14, v6, v7
	s_addc_u32 s5, s9, s5
	v_mov_b32_e32 v15, v0
	v_mov_b32_e32 v16, v0
	v_mov_b32_e32 v17, v0
	global_store_dwordx4 v0, v[14:17], s[4:5]
	s_branch .LBB0_937
